# dif attention tile loop: 28 register copies per tile removed from the common (no-rescale) path; exps read the score registers directly
# speedup vs baseline: 1.0066x; 1.0066x over previous
; __device__ __forceinline__ float ex2(float x) { return __builtin_amdgcn_exp2f(x); }
; __device__ __forceinline__ void attn_dif_unit(LAS unsigned char* lds, const int tid, const int wave_s, const bf16_t* q, const bf16_t* k0, const bf16_t* k1, const bf16_t* vt0, const bf16_t* vt1, ...
;     ...
;             if (t == 0 || __any(mx > DA_THR)) {
;                 const float delta = t == 0 ? mx : fmaxf(mx, 0.f), alpha = t == 0 ? 1.f : ex2(-delta);
;                 m_used[m] += delta; l_run[m] *= alpha;
; #pragma unroll
;                 for (int i = 0; i < 4; ++i)
; #pragma unroll
;                     for (int r = 0; r < 16; ++r) oacc[m][i][r] *= alpha;
; #pragma unroll
;                 for (int a = 0; a < 2; ++a)
; #pragma unroll
;                     for (int r = 0; r < 16; ++r) sacc[a][r] -= delta;
;             }
.LBB0_992:
	s_and_b64 vcc, exec, s[14:15]
	s_cbranch_vccnz .LBB0_994
	s_branch .LBB0_995

; __device__ __forceinline__ float ex2(float x) { return __builtin_amdgcn_exp2f(x); }
; __device__ __forceinline__ void attn_dif_unit(LAS unsigned char* lds, const int tid, const int wave_s, const bf16_t* q, const bf16_t* k0, const bf16_t* k1, const bf16_t* vt0, const bf16_t* vt1, ...
;     ...
;             if (t == 0 || __any(mx > DA_THR)) {
;                 const float delta = t == 0 ? mx : fmaxf(mx, 0.f), alpha = t == 0 ? 1.f : ex2(-delta);
;                 m_used[m] += delta; l_run[m] *= alpha;
; #pragma unroll
;                 for (int i = 0; i < 4; ++i)
; #pragma unroll
;                     for (int r = 0; r < 16; ++r) oacc[m][i][r] *= alpha;
; #pragma unroll
;                 for (int a = 0; a < 2; ++a)
; #pragma unroll
;                     for (int r = 0; r < 16; ++r) sacc[a][r] -= delta;
;             }
.LBB0_995:
	s_andn2_b64 vcc, exec, s[12:13]
	s_cbranch_vccnz .LBB0_997
	v_exp_f32_e64 v10, -v0
	v_mov_b32_e32 v3, v162
	v_mov_b32_e32 v4, v163
	v_mov_b32_e32 v6, v165
	v_mov_b32_e32 v7, v166
	v_mov_b32_e32 v162, v169
	v_mov_b32_e32 v163, v170
	v_cndmask_b32_e64 v10, v10, 1.0, s[6:7]
	v_mov_b32_e32 v5, v164
	v_mov_b32_e32 v164, v171
	v_mov_b32_e32 v165, v172
	v_mul_f32_e32 v219, v219, v10
	v_pk_mul_f32 v[142:143], v[142:143], v[10:11] op_sel_hi:[1,0]
	v_pk_mul_f32 v[140:141], v[140:141], v[10:11] op_sel_hi:[1,0]
	v_pk_mul_f32 v[138:139], v[138:139], v[10:11] op_sel_hi:[1,0]
	v_pk_mul_f32 v[136:137], v[136:137], v[10:11] op_sel_hi:[1,0]
	v_pk_mul_f32 v[134:135], v[134:135], v[10:11] op_sel_hi:[1,0]
	v_pk_mul_f32 v[132:133], v[132:133], v[10:11] op_sel_hi:[1,0]
	v_pk_mul_f32 v[130:131], v[130:131], v[10:11] op_sel_hi:[1,0]
	v_pk_mul_f32 v[128:129], v[128:129], v[10:11] op_sel_hi:[1,0]
	v_pk_mul_f32 v[110:111], v[110:111], v[10:11] op_sel_hi:[1,0]
	v_pk_mul_f32 v[108:109], v[108:109], v[10:11] op_sel_hi:[1,0]
	v_pk_mul_f32 v[106:107], v[106:107], v[10:11] op_sel_hi:[1,0]
	v_pk_mul_f32 v[104:105], v[104:105], v[10:11] op_sel_hi:[1,0]
	v_pk_mul_f32 v[102:103], v[102:103], v[10:11] op_sel_hi:[1,0]
	v_pk_mul_f32 v[100:101], v[100:101], v[10:11] op_sel_hi:[1,0]
	v_pk_mul_f32 v[98:99], v[98:99], v[10:11] op_sel_hi:[1,0]
	v_pk_mul_f32 v[96:97], v[96:97], v[10:11] op_sel_hi:[1,0]
	v_pk_mul_f32 v[78:79], v[78:79], v[10:11] op_sel_hi:[1,0]
	v_pk_mul_f32 v[76:77], v[76:77], v[10:11] op_sel_hi:[1,0]
	v_pk_mul_f32 v[74:75], v[74:75], v[10:11] op_sel_hi:[1,0]
	v_pk_mul_f32 v[72:73], v[72:73], v[10:11] op_sel_hi:[1,0]
	v_pk_mul_f32 v[70:71], v[70:71], v[10:11] op_sel_hi:[1,0]
	v_pk_mul_f32 v[68:69], v[68:69], v[10:11] op_sel_hi:[1,0]
	v_pk_mul_f32 v[66:67], v[66:67], v[10:11] op_sel_hi:[1,0]
	v_pk_mul_f32 v[64:65], v[64:65], v[10:11] op_sel_hi:[1,0]
	v_pk_mul_f32 v[46:47], v[46:47], v[10:11] op_sel_hi:[1,0]
	v_pk_mul_f32 v[44:45], v[44:45], v[10:11] op_sel_hi:[1,0]
	v_pk_mul_f32 v[42:43], v[42:43], v[10:11] op_sel_hi:[1,0]
	v_pk_mul_f32 v[40:41], v[40:41], v[10:11] op_sel_hi:[1,0]
	v_pk_mul_f32 v[38:39], v[38:39], v[10:11] op_sel_hi:[1,0]
	v_pk_mul_f32 v[36:37], v[36:37], v[10:11] op_sel_hi:[1,0]
	v_pk_mul_f32 v[34:35], v[34:35], v[10:11] op_sel_hi:[1,0]
	v_pk_mul_f32 v[32:33], v[32:33], v[10:11] op_sel_hi:[1,0]
	v_pk_add_f32 v[10:11], v[6:7], v[0:1] op_sel_hi:[1,0] neg_lo:[0,1] neg_hi:[0,1]
	v_pk_add_f32 v[6:7], v[162:163], v[0:1] op_sel_hi:[1,0] neg_lo:[0,1] neg_hi:[0,1]
	v_pk_mov_b32 v[162:163], v[174:175], v[144:145] op_sel:[1,0]
	v_mov_b32_e32 v144, v145
	v_mov_b32_e32 v145, v146
	v_mov_b32_e32 v2, v161
	v_mov_b32_e32 v8, v167
	v_mov_b32_e32 v166, v173
	v_mov_b32_e32 v167, v174
	v_pk_add_f32 v[12:13], v[4:5], v[0:1] op_sel_hi:[1,0] neg_lo:[0,1] neg_hi:[0,1]
	v_pk_add_f32 v[4:5], v[164:165], v[0:1] op_sel_hi:[1,0] neg_lo:[0,1] neg_hi:[0,1]
	v_pk_add_f32 v[164:165], v[144:145], v[0:1] op_sel_hi:[1,0] neg_lo:[0,1] neg_hi:[0,1]
	v_mov_b32_e32 v144, v147
	v_mov_b32_e32 v145, v148
	v_pk_add_f32 v[14:15], v[2:3], v[0:1] op_sel_hi:[1,0] neg_lo:[0,1] neg_hi:[0,1]
	v_pk_add_f32 v[2:3], v[166:167], v[0:1] op_sel_hi:[1,0] neg_lo:[0,1] neg_hi:[0,1]
	v_pk_add_f32 v[166:167], v[144:145], v[0:1] op_sel_hi:[1,0] neg_lo:[0,1] neg_hi:[0,1]
	v_mov_b32_e32 v144, v149
	v_mov_b32_e32 v145, v150
	v_mov_b32_e32 v9, v168
	v_pk_add_f32 v[168:169], v[144:145], v[0:1] op_sel_hi:[1,0] neg_lo:[0,1] neg_hi:[0,1]
	v_mov_b32_e32 v144, v151
	v_mov_b32_e32 v145, v152
	v_pk_add_f32 v[170:171], v[144:145], v[0:1] op_sel_hi:[1,0] neg_lo:[0,1] neg_hi:[0,1]
	v_mov_b32_e32 v144, v153
	v_mov_b32_e32 v145, v154
	v_pk_add_f32 v[172:173], v[144:145], v[0:1] op_sel_hi:[1,0] neg_lo:[0,1] neg_hi:[0,1]
	v_mov_b32_e32 v144, v155
	v_mov_b32_e32 v145, v156
	v_pk_add_f32 v[192:193], v[144:145], v[0:1] op_sel_hi:[1,0] neg_lo:[0,1] neg_hi:[0,1]
	v_mov_b32_e32 v144, v157
	v_mov_b32_e32 v145, v158
	v_pk_add_f32 v[162:163], v[162:163], v[0:1] op_sel_hi:[1,0] neg_lo:[0,1] neg_hi:[0,1]
	v_pk_add_f32 v[194:195], v[144:145], v[0:1] op_sel_hi:[1,0] neg_lo:[0,1] neg_hi:[0,1]
	v_add_f32_e32 v218, v218, v0
	v_sub_f32_e32 v160, v160, v0
	v_pk_add_f32 v[8:9], v[8:9], v[0:1] op_sel_hi:[1,0] neg_lo:[0,1] neg_hi:[0,1]
	v_sub_f32_e32 v159, v159, v0
	v_mov_b32_e32 v175, v162
	v_mov_b32_e32 v144, v163
	v_mov_b32_e32 v145, v164
	v_mov_b32_e32 v146, v165
	v_mov_b32_e32 v147, v166
	v_mov_b32_e32 v148, v167
	v_mov_b32_e32 v149, v168
	v_mov_b32_e32 v150, v169
	v_mov_b32_e32 v151, v170
	v_mov_b32_e32 v152, v171
	v_mov_b32_e32 v153, v172
	v_mov_b32_e32 v154, v173
	v_mov_b32_e32 v155, v192
	v_mov_b32_e32 v156, v193
	v_mov_b32_e32 v157, v194
	v_mov_b32_e32 v158, v195
	v_mov_b32_e32 v161, v14
	v_mov_b32_e32 v162, v15
	v_mov_b32_e32 v163, v12
	v_mov_b32_e32 v164, v13
	v_mov_b32_e32 v165, v10
	v_mov_b32_e32 v166, v11
	v_mov_b32_e32 v167, v8
	v_mov_b32_e32 v168, v9
	v_mov_b32_e32 v169, v6
	v_mov_b32_e32 v170, v7
	v_mov_b32_e32 v171, v4
	v_mov_b32_e32 v172, v5
	v_mov_b32_e32 v173, v2
	v_mov_b32_e32 v174, v3
; __device__ __forceinline__ void attn_dif_unit(LAS unsigned char* lds, const int tid, const int wave_s, const bf16_t* q, const bf16_t* k0, const bf16_t* k1, const bf16_t* vt0, const bf16_t* vt1, ...
;     ...
;             f32x16 sacc[2]; const float nm = -m_used[m];
;             {
;                 bf16x8 qf[4], kfa[4], kfb[4];
; #pragma unroll
;                 for (int ks = 0; ks < 4; ++ks) qf[ks] = *(const LAS bf16x8*)(qb + c32 * DA_KP + m * 128 + ks * 32 + hi * 16);
; #pragma unroll
;                 for (int ks = 0; ks < 4; ++ks) kfa[ks] = *(const LAS bf16x8*)(kb + c32 * DA_KP + m * 128 + ks * 32 + hi * 16);
; #pragma unroll
;                 for (int ks = 0; ks < 4; ++ks) kfb[ks] = *(const LAS bf16x8*)(kb + (32 + c32) * DA_KP + m * 128 + ks * 32 + hi * 16);
; #pragma unroll
;                 for (int r = 0; r < 16; ++r) { sacc[0][r] = nm; sacc[1][r] = nm; }
; #pragma unroll
;                 for (int ks = 0; ks < 4; ++ks) sacc[0] = __builtin_amdgcn_mfma_f32_32x32x16_bf16(kfa[ks], qf[ks], sacc[0], 0, 0, 0);
; #pragma unroll
;                 for (int ks = 0; ks < 4; ++ks) sacc[1] = __builtin_amdgcn_mfma_f32_32x32x16_bf16(kfb[ks], qf[ks], sacc[1], 0, 0, 0);
;             }
;             float mx = fmaxf(sacc[0][0], sacc[1][0]);
; #pragma unroll
;             for (int a = 0; a < 2; ++a)
; #pragma unroll
;     ...
;             float ls = 0.f;
; #pragma unroll
;             for (int a = 0; a < 2; ++a)
; #pragma unroll
;                 for (int r = 0; r < 16; ++r) { const float p = ex2(sacc[a][r]); sacc[a][r] = p; ls += p; }
;             l_run[m] += ls;
;             bf16x8 pf[4];
; #pragma unroll
;             for (int a = 0; a < 2; ++a)
; #pragma unroll
;                 for (int jj = 0; jj < 2; ++jj) { u32x4 wv; wv.x = cvt_pk_bf16(sacc[a][8 * jj + 0], sacc[a][8 * jj + 1]); wv.y = cvt_pk_bf16(sacc[a][8 * jj + 2], sacc[a][8 * jj + 3]);
;                     wv.z = cvt_pk_bf16(sacc[a][8 * jj + 4], sacc[a][8 * jj + 5]); wv.w = cvt_pk_bf16(sacc[a][8 * jj + 6], sacc[a][8 * jj + 7]); pf[2 * a + jj] = __builtin_bit_cast(bf16x8, wv); }
;             if (m == 1 && t + 1 < ntile) DA_LOAD(t + 1);
;             {
;                 const LAS unsigned char* vp0 = vb + c32 * DA_VP + hi * 16;
;     ...
;                 bf16x8 va[4], vc[4];
;                 DA_VF(va, 0); DA_VF(vc, 1); DA_PV(va, 0); DA_VF(va, 2); DA_PV(vc, 1); DA_VF(vc, 3); DA_PV(va, 2); DA_PV(vc, 3);
.LBB0_997:
	v_mul_u32_u24_e32 v0, 0x90, v208
	v_add_u32_e32 v0, s22, v0
	v_add_u32_e32 v220, v0, v213
	v_exp_f32_e32 v221, v160
	v_exp_f32_e32 v222, v161
	v_exp_f32_e32 v223, v162
	v_exp_f32_e32 v224, v163
	v_exp_f32_e32 v225, v164
	v_exp_f32_e32 v226, v165
	v_exp_f32_e32 v227, v166
	v_exp_f32_e32 v228, v167
	v_exp_f32_e32 v229, v168
	v_exp_f32_e32 v230, v169
	v_exp_f32_e32 v231, v170
	v_exp_f32_e32 v232, v171
	v_exp_f32_e32 v233, v172
	v_exp_f32_e32 v234, v173
	v_exp_f32_e32 v235, v174
	v_exp_f32_e32 v236, v175
	v_exp_f32_e32 v237, v144
	v_exp_f32_e32 v238, v145
	v_exp_f32_e32 v239, v146
	v_exp_f32_e32 v247, v147
	v_exp_f32_e32 v241, v148
	v_exp_f32_e32 v243, v149
	v_exp_f32_e32 v240, v150
	v_exp_f32_e32 v192, v151
	v_exp_f32_e32 v193, v152
	v_exp_f32_e32 v194, v153
	v_exp_f32_e32 v195, v154
	v_exp_f32_e32 v196, v155
	v_exp_f32_e32 v197, v156
	v_exp_f32_e32 v242, v157
	v_exp_f32_e32 v250, v158
	v_exp_f32_e32 v251, v159
	ds_read_b128 v[148:151], v220 offset:17408
	ds_read_b128 v[152:155], v220 offset:17440
	ds_read_b128 v[156:159], v220 offset:17472
	ds_read_b128 v[160:163], v220 offset:17504
	ds_read_b128 v[164:167], v220 offset:22016
	ds_read_b128 v[168:171], v220 offset:22048
	v_cvt_pk_bf16_f32 v2, v221, v222
	v_cvt_pk_bf16_f32 v3, v223, v224
	v_cvt_pk_bf16_f32 v4, v225, v226
	v_cvt_pk_bf16_f32 v5, v227, v228
	v_cvt_pk_bf16_f32 v6, v229, v230
	v_cvt_pk_bf16_f32 v7, v231, v232
	v_cvt_pk_bf16_f32 v8, v233, v234
	v_cvt_pk_bf16_f32 v9, v235, v236
	v_cvt_pk_bf16_f32 v10, v237, v238
	v_cvt_pk_bf16_f32 v11, v239, v247
	v_cvt_pk_bf16_f32 v12, v241, v243
	v_cvt_pk_bf16_f32 v13, v240, v192
	v_cvt_pk_bf16_f32 v144, v193, v194
	v_cvt_pk_bf16_f32 v145, v195, v196
	v_cvt_pk_bf16_f32 v146, v197, v242
	v_cvt_pk_bf16_f32 v147, v250, v251
	s_waitcnt lgkmcnt(5)
	v_mfma_f32_32x32x16_bf16 v[128:143], v[148:151], v[2:5], v[128:143]
	ds_read_b128 v[172:175], v220 offset:22080
	s_waitcnt lgkmcnt(5)
	v_mfma_f32_32x32x16_bf16 v[128:143], v[152:155], v[6:9], v[128:143]
	ds_read_b128 v[148:151], v220 offset:22112
	s_waitcnt lgkmcnt(5)
	v_mfma_f32_32x32x16_bf16 v[128:143], v[156:159], v[10:13], v[128:143]
	ds_read_b128 v[152:155], v220 offset:26624
	s_waitcnt lgkmcnt(5)
	v_mfma_f32_32x32x16_bf16 v[128:143], v[160:163], v[144:147], v[128:143]
	ds_read_b128 v[156:159], v220 offset:26656
	s_waitcnt lgkmcnt(5)
	v_mfma_f32_32x32x16_bf16 v[96:111], v[164:167], v[2:5], v[96:111]
	ds_read_b128 v[160:163], v220 offset:26688
	s_waitcnt lgkmcnt(5)
	v_mfma_f32_32x32x16_bf16 v[96:111], v[168:171], v[6:9], v[96:111]
	ds_read_b128 v[164:167], v220 offset:26720
	s_waitcnt lgkmcnt(5)
	v_mfma_f32_32x32x16_bf16 v[96:111], v[172:175], v[10:13], v[96:111]
	ds_read_b128 v[168:171], v220 offset:31232
	s_waitcnt lgkmcnt(5)
	v_mfma_f32_32x32x16_bf16 v[96:111], v[148:151], v[144:147], v[96:111]
	ds_read_b128 v[172:175], v220 offset:31264
	s_waitcnt lgkmcnt(5)
	v_mfma_f32_32x32x16_bf16 v[64:79], v[152:155], v[2:5], v[64:79]
	ds_read_b128 v[148:151], v220 offset:31296
	s_waitcnt lgkmcnt(5)
	v_mfma_f32_32x32x16_bf16 v[64:79], v[156:159], v[6:9], v[64:79]
	ds_read_b128 v[152:155], v220 offset:31328
	s_waitcnt lgkmcnt(5)
	v_mfma_f32_32x32x16_bf16 v[64:79], v[160:163], v[10:13], v[64:79]
	s_waitcnt lgkmcnt(4)
	v_mfma_f32_32x32x16_bf16 v[64:79], v[164:167], v[144:147], v[64:79]
	s_waitcnt lgkmcnt(3)
	v_mfma_f32_32x32x16_bf16 v[32:47], v[168:171], v[2:5], v[32:47]
	s_waitcnt lgkmcnt(2)
	v_mfma_f32_32x32x16_bf16 v[32:47], v[172:175], v[6:9], v[32:47]
	s_waitcnt lgkmcnt(1)
	v_mfma_f32_32x32x16_bf16 v[32:47], v[148:151], v[10:13], v[32:47]
	s_waitcnt lgkmcnt(0)
	v_mfma_f32_32x32x16_bf16 v[32:47], v[152:155], v[144:147], v[32:47]
	ds_read_b128 v[2:5], v215 offset:128
	ds_read_b128 v[6:9], v252 offset:128
	v_xor_b32_e32 v144, 0x80000000, v217
	v_mov_b32_e32 v145, v144
	v_mov_b32_e32 v146, v144
	v_mov_b32_e32 v147, v144
	v_mov_b32_e32 v148, v144
	v_mov_b32_e32 v149, v144
	v_mov_b32_e32 v150, v144
	v_mov_b32_e32 v151, v144
	v_mov_b32_e32 v152, v144
	v_mov_b32_e32 v153, v144
	v_mov_b32_e32 v154, v144
	v_mov_b32_e32 v155, v144
	v_mov_b32_e32 v156, v144
	v_mov_b32_e32 v157, v144
	v_mov_b32_e32 v158, v144
	v_mov_b32_e32 v159, v144
	s_and_b64 vcc, exec, s[10:11]
	s_waitcnt lgkmcnt(0)
	v_mfma_f32_32x32x16_bf16 v[160:175], v[6:9], v[2:5], v[144:159]
	ds_read_b128 v[6:9], v252 offset:160
	ds_read_b128 v[10:13], v215 offset:160
	s_waitcnt lgkmcnt(0)
	v_mfma_f32_32x32x16_bf16 v[160:175], v[6:9], v[10:13], v[160:175]
	ds_read_b128 v[6:9], v252 offset:192
	ds_read_b128 v[204:207], v215 offset:192
	s_waitcnt lgkmcnt(0)
	v_mfma_f32_32x32x16_bf16 v[160:175], v[6:9], v[204:207], v[160:175]
	ds_read_b128 v[6:9], v252 offset:8832
	s_waitcnt lgkmcnt(0)
	v_mfma_f32_32x32x16_bf16 v[144:159], v[6:9], v[2:5], v[144:159]
	ds_read_b128 v[2:5], v252 offset:8864
	s_waitcnt lgkmcnt(0)
	v_mfma_f32_32x32x16_bf16 v[144:159], v[2:5], v[10:13], v[144:159]
	ds_read_b128 v[2:5], v252 offset:8896
	s_waitcnt lgkmcnt(0)
	v_mfma_f32_32x32x16_bf16 v[144:159], v[2:5], v[204:207], v[144:159]
	ds_read_b128 v[2:5], v252 offset:8928
	ds_read_b128 v[6:9], v215 offset:224
	s_waitcnt lgkmcnt(0)
	v_mfma_f32_32x32x16_bf16 v[144:159], v[2:5], v[6:9], v[144:159]
	ds_read_b128 v[2:5], v252 offset:224
	s_waitcnt lgkmcnt(0)
	v_mfma_f32_32x32x16_bf16 v[160:175], v[2:5], v[6:9], v[160:175]
	s_nop 8
	v_max_f32_e32 v0, v144, v144
	s_nop 1
	v_max_f32_e32 v2, v160, v160
	v_max_f32_e32 v0, v2, v0
	v_max3_f32 v0, v0, v161, v162
	v_max3_f32 v0, v0, v163, v164
	v_max3_f32 v0, v0, v165, v166
	v_max3_f32 v0, v0, v167, v168
	v_max3_f32 v0, v0, v169, v170
	v_max3_f32 v0, v0, v171, v172
	v_max3_f32 v0, v0, v173, v174
	v_max3_f32 v0, v0, v175, v145
	v_max3_f32 v0, v0, v146, v147
	v_max3_f32 v0, v0, v148, v149
	v_max3_f32 v0, v0, v150, v151
	v_max3_f32 v0, v0, v152, v153
	v_max3_f32 v0, v0, v154, v155
	v_max3_f32 v0, v0, v156, v157
	v_max3_f32 v0, v0, v158, v159
	ds_bpermute_b32 v2, v203, v0
	s_waitcnt lgkmcnt(0)
	v_max_f32_e32 v2, v2, v2
	v_max_f32_e32 v252, v0, v2
	s_cbranch_vccz .LBB0_1001
	v_cmp_lt_f32_e32 vcc, s64, v252
	s_mov_b64 s[12:13], 0
	s_mov_b64 s[10:11], 0
	s_cbranch_vccz .LBB0_1000
	v_max_f32_e32 v0, v252, v252
	v_max_f32_e32 v0, 0, v0
	s_mov_b64 s[10:11], -1
.LBB0_1000:
	s_and_b64 vcc, exec, s[12:13]
	s_cbranch_vccnz .LBB0_1002
	s_branch .LBB0_1003

; __device__ __forceinline__ unsigned cvt_pk_bf16(float lo, float hi) { unsigned r; asm volatile("v_cvt_pk_bf16_f32 %0, %1, %2" : "=v"(r) : "v"(lo), "v"(hi)); return r; }
; __device__ __forceinline__ float ex2(float x) { return __builtin_amdgcn_exp2f(x); }
; __device__ __forceinline__ void attn_dif_unit(LAS unsigned char* lds, const int tid, const int wave_s, const bf16_t* q, const bf16_t* k0, const bf16_t* k1, const bf16_t* vt0, const bf16_t* vt1, ...
;     ...
;             if (t == 0 || __any(mx > DA_THR)) {
;                 const float delta = t == 0 ? mx : fmaxf(mx, 0.f), alpha = t == 0 ? 1.f : ex2(-delta);
;                 m_used[m] += delta; l_run[m] *= alpha;
; #pragma unroll
;                 for (int i = 0; i < 4; ++i)
; #pragma unroll
;                     for (int r = 0; r < 16; ++r) oacc[m][i][r] *= alpha;
; #pragma unroll
;                 for (int a = 0; a < 2; ++a)
; #pragma unroll
;                     for (int r = 0; r < 16; ++r) sacc[a][r] -= delta;
;             }
;             float ls = 0.f;
; #pragma unroll
;             for (int a = 0; a < 2; ++a)
; #pragma unroll
;                 for (int r = 0; r < 16; ++r) { const float p = ex2(sacc[a][r]); sacc[a][r] = p; ls += p; }
;             l_run[m] += ls;
;             bf16x8 pf[4];
; #pragma unroll
;             for (int a = 0; a < 2; ++a)
; #pragma unroll
;                 for (int jj = 0; jj < 2; ++jj) { u32x4 wv; wv.x = cvt_pk_bf16(sacc[a][8 * jj + 0], sacc[a][8 * jj + 1]); wv.y = cvt_pk_bf16(sacc[a][8 * jj + 2], sacc[a][8 * jj + 3]);
;                     wv.z = cvt_pk_bf16(sacc[a][8 * jj + 4], sacc[a][8 * jj + 5]); wv.w = cvt_pk_bf16(sacc[a][8 * jj + 6], sacc[a][8 * jj + 7]); pf[2 * a + jj] = __builtin_bit_cast(bf16x8, wv); }
.LBB0_1003:
	s_andn2_b64 vcc, exec, s[10:11]
	s_cbranch_vccnz .LBB0_1005
	v_exp_f32_e64 v10, -v0
	v_mov_b32_e32 v3, v162
	v_mov_b32_e32 v4, v163
	v_mov_b32_e32 v6, v165
	v_mov_b32_e32 v7, v166
	v_mov_b32_e32 v162, v169
	v_mov_b32_e32 v163, v170
	v_cndmask_b32_e64 v10, v10, 1.0, s[6:7]
	v_mov_b32_e32 v5, v164
	v_mov_b32_e32 v164, v171
	v_mov_b32_e32 v165, v172
	v_mul_f32_e32 v216, v216, v10
	v_pk_mul_f32 v[126:127], v[126:127], v[10:11] op_sel_hi:[1,0]
	v_pk_mul_f32 v[124:125], v[124:125], v[10:11] op_sel_hi:[1,0]
	v_pk_mul_f32 v[122:123], v[122:123], v[10:11] op_sel_hi:[1,0]
	v_pk_mul_f32 v[120:121], v[120:121], v[10:11] op_sel_hi:[1,0]
	v_pk_mul_f32 v[118:119], v[118:119], v[10:11] op_sel_hi:[1,0]
	v_pk_mul_f32 v[116:117], v[116:117], v[10:11] op_sel_hi:[1,0]
	v_pk_mul_f32 v[114:115], v[114:115], v[10:11] op_sel_hi:[1,0]
	v_pk_mul_f32 v[112:113], v[112:113], v[10:11] op_sel_hi:[1,0]
	v_pk_mul_f32 v[94:95], v[94:95], v[10:11] op_sel_hi:[1,0]
	v_pk_mul_f32 v[92:93], v[92:93], v[10:11] op_sel_hi:[1,0]
	v_pk_mul_f32 v[90:91], v[90:91], v[10:11] op_sel_hi:[1,0]
	v_pk_mul_f32 v[88:89], v[88:89], v[10:11] op_sel_hi:[1,0]
	v_pk_mul_f32 v[86:87], v[86:87], v[10:11] op_sel_hi:[1,0]
	v_pk_mul_f32 v[84:85], v[84:85], v[10:11] op_sel_hi:[1,0]
	v_pk_mul_f32 v[82:83], v[82:83], v[10:11] op_sel_hi:[1,0]
	v_pk_mul_f32 v[80:81], v[80:81], v[10:11] op_sel_hi:[1,0]
	v_pk_mul_f32 v[62:63], v[62:63], v[10:11] op_sel_hi:[1,0]
	v_pk_mul_f32 v[60:61], v[60:61], v[10:11] op_sel_hi:[1,0]
	v_pk_mul_f32 v[58:59], v[58:59], v[10:11] op_sel_hi:[1,0]
	v_pk_mul_f32 v[56:57], v[56:57], v[10:11] op_sel_hi:[1,0]
	v_pk_mul_f32 v[54:55], v[54:55], v[10:11] op_sel_hi:[1,0]
	v_pk_mul_f32 v[52:53], v[52:53], v[10:11] op_sel_hi:[1,0]
	v_pk_mul_f32 v[50:51], v[50:51], v[10:11] op_sel_hi:[1,0]
	v_pk_mul_f32 v[48:49], v[48:49], v[10:11] op_sel_hi:[1,0]
	v_pk_mul_f32 v[30:31], v[30:31], v[10:11] op_sel_hi:[1,0]
	v_pk_mul_f32 v[28:29], v[28:29], v[10:11] op_sel_hi:[1,0]
	v_pk_mul_f32 v[26:27], v[26:27], v[10:11] op_sel_hi:[1,0]
	v_pk_mul_f32 v[24:25], v[24:25], v[10:11] op_sel_hi:[1,0]
	v_pk_mul_f32 v[22:23], v[22:23], v[10:11] op_sel_hi:[1,0]
	v_pk_mul_f32 v[20:21], v[20:21], v[10:11] op_sel_hi:[1,0]
	v_pk_mul_f32 v[18:19], v[18:19], v[10:11] op_sel_hi:[1,0]
	v_pk_mul_f32 v[16:17], v[16:17], v[10:11] op_sel_hi:[1,0]
	v_pk_add_f32 v[10:11], v[6:7], v[0:1] op_sel_hi:[1,0] neg_lo:[0,1] neg_hi:[0,1]
	v_pk_add_f32 v[6:7], v[162:163], v[0:1] op_sel_hi:[1,0] neg_lo:[0,1] neg_hi:[0,1]
	v_pk_mov_b32 v[162:163], v[174:175], v[144:145] op_sel:[1,0]
	v_mov_b32_e32 v144, v145
	v_mov_b32_e32 v145, v146
	v_mov_b32_e32 v2, v161
	v_mov_b32_e32 v8, v167
	v_mov_b32_e32 v166, v173
	v_mov_b32_e32 v167, v174
	v_pk_add_f32 v[12:13], v[4:5], v[0:1] op_sel_hi:[1,0] neg_lo:[0,1] neg_hi:[0,1]
	v_pk_add_f32 v[4:5], v[164:165], v[0:1] op_sel_hi:[1,0] neg_lo:[0,1] neg_hi:[0,1]
	v_pk_add_f32 v[164:165], v[144:145], v[0:1] op_sel_hi:[1,0] neg_lo:[0,1] neg_hi:[0,1]
	v_mov_b32_e32 v144, v147
	v_mov_b32_e32 v145, v148
	v_pk_add_f32 v[14:15], v[2:3], v[0:1] op_sel_hi:[1,0] neg_lo:[0,1] neg_hi:[0,1]
	v_pk_add_f32 v[2:3], v[166:167], v[0:1] op_sel_hi:[1,0] neg_lo:[0,1] neg_hi:[0,1]
	v_pk_add_f32 v[166:167], v[144:145], v[0:1] op_sel_hi:[1,0] neg_lo:[0,1] neg_hi:[0,1]
	v_mov_b32_e32 v144, v149
	v_mov_b32_e32 v145, v150
	v_mov_b32_e32 v9, v168
	v_pk_add_f32 v[168:169], v[144:145], v[0:1] op_sel_hi:[1,0] neg_lo:[0,1] neg_hi:[0,1]
	v_mov_b32_e32 v144, v151
	v_mov_b32_e32 v145, v152
	v_pk_add_f32 v[170:171], v[144:145], v[0:1] op_sel_hi:[1,0] neg_lo:[0,1] neg_hi:[0,1]
	v_mov_b32_e32 v144, v153
	v_mov_b32_e32 v145, v154
	v_pk_add_f32 v[172:173], v[144:145], v[0:1] op_sel_hi:[1,0] neg_lo:[0,1] neg_hi:[0,1]
	v_mov_b32_e32 v144, v155
	v_mov_b32_e32 v145, v156
	v_pk_add_f32 v[204:205], v[144:145], v[0:1] op_sel_hi:[1,0] neg_lo:[0,1] neg_hi:[0,1]
	v_mov_b32_e32 v144, v157
	v_mov_b32_e32 v145, v158
	v_pk_add_f32 v[162:163], v[162:163], v[0:1] op_sel_hi:[1,0] neg_lo:[0,1] neg_hi:[0,1]
	v_pk_add_f32 v[206:207], v[144:145], v[0:1] op_sel_hi:[1,0] neg_lo:[0,1] neg_hi:[0,1]
	v_add_f32_e32 v217, v217, v0
	v_sub_f32_e32 v160, v160, v0
	v_pk_add_f32 v[8:9], v[8:9], v[0:1] op_sel_hi:[1,0] neg_lo:[0,1] neg_hi:[0,1]
	v_sub_f32_e32 v159, v159, v0
	v_mov_b32_e32 v175, v162
	v_mov_b32_e32 v144, v163
	v_mov_b32_e32 v145, v164
	v_mov_b32_e32 v146, v165
	v_mov_b32_e32 v147, v166
	v_mov_b32_e32 v148, v167
	v_mov_b32_e32 v149, v168
	v_mov_b32_e32 v150, v169
	v_mov_b32_e32 v151, v170
	v_mov_b32_e32 v152, v171
	v_mov_b32_e32 v153, v172
	v_mov_b32_e32 v154, v173
	v_mov_b32_e32 v155, v204
	v_mov_b32_e32 v156, v205
	v_mov_b32_e32 v157, v206
	v_mov_b32_e32 v158, v207
	v_mov_b32_e32 v161, v14
	v_mov_b32_e32 v162, v15
	v_mov_b32_e32 v163, v12
	v_mov_b32_e32 v164, v13
	v_mov_b32_e32 v165, v10
	v_mov_b32_e32 v166, v11
	v_mov_b32_e32 v167, v8
	v_mov_b32_e32 v168, v9
	v_mov_b32_e32 v169, v6
	v_mov_b32_e32 v170, v7
	v_mov_b32_e32 v171, v4
	v_mov_b32_e32 v172, v5
	v_mov_b32_e32 v173, v2
	v_mov_b32_e32 v174, v3
.LBB0_1005:
	v_exp_f32_e32 v0, v160
	v_exp_f32_e32 v14, v161
	v_exp_f32_e32 v15, v162
	v_exp_f32_e32 v160, v163
	v_exp_f32_e32 v161, v164
	v_exp_f32_e32 v162, v165
	v_exp_f32_e32 v163, v166
	v_exp_f32_e32 v164, v167
	v_exp_f32_e32 v165, v168
	v_exp_f32_e32 v166, v169
	v_exp_f32_e32 v167, v170
	v_exp_f32_e32 v168, v171
	v_exp_f32_e32 v169, v172
	v_exp_f32_e32 v170, v173
	v_exp_f32_e32 v171, v174
	v_exp_f32_e32 v172, v175
	v_exp_f32_e32 v173, v144
	v_exp_f32_e32 v174, v145
	v_exp_f32_e32 v175, v146
	v_exp_f32_e32 v252, v147
	v_exp_f32_e32 v148, v148
	v_exp_f32_e32 v149, v149
	v_exp_f32_e32 v150, v150
	v_exp_f32_e32 v151, v151
	v_exp_f32_e32 v152, v152
	v_exp_f32_e32 v153, v153
	v_exp_f32_e32 v154, v154
	v_exp_f32_e32 v155, v155
	v_exp_f32_e32 v156, v156
	v_exp_f32_e32 v157, v157
	v_exp_f32_e32 v158, v158
	v_exp_f32_e32 v159, v159
	s_cmp_ge_u32 s55, s49
	v_cvt_pk_bf16_f32 v144, v0, v14
	v_cvt_pk_bf16_f32 v145, v15, v160
	v_cvt_pk_bf16_f32 v146, v161, v162
	v_cvt_pk_bf16_f32 v147, v163, v164
	v_cvt_pk_bf16_f32 v10, v165, v166
	v_cvt_pk_bf16_f32 v11, v167, v168
	v_cvt_pk_bf16_f32 v12, v169, v170
	v_cvt_pk_bf16_f32 v13, v171, v172
	v_cvt_pk_bf16_f32 v6, v173, v174
	v_cvt_pk_bf16_f32 v7, v175, v252
	v_cvt_pk_bf16_f32 v8, v148, v149
	v_cvt_pk_bf16_f32 v9, v150, v151
	v_cvt_pk_bf16_f32 v2, v152, v153
	v_cvt_pk_bf16_f32 v3, v154, v155
	v_cvt_pk_bf16_f32 v4, v156, v157
	v_cvt_pk_bf16_f32 v5, v158, v159
	s_branch .LBB0_986
